# DPP strategy: SSD per-chunk decay cumsum uses a DPP row_shr/row_bcast wave scan (f32, reassociated) instead of six ds_bpermute round trips on wave 0
# baseline (speedup 1.0000x reference)
; __device__ __forceinline__ u32x2 pack4(f32x4 v) { u32x2 r; r.x = cvt_pk(v[0], v[1]); r.y = cvt_pk(v[2], v[3]); return r; }
; __device__ __forceinline__ float shfl_idx_f(float v, int src) { return __int_as_float(__builtin_amdgcn_ds_bpermute(src << 2, __float_as_int(v))); }
; __device__ __forceinline__ void ssd_prompt_item(const Params& p, int item, const int wv) {
;     ...
;     for (int pb = 0; pb < 4; ++pb) *(u32x2*)(h_l + (pb * 16 + fr) * 136 + wid * 16 + fq * 4) = pack4(hacc[pb]);
;     if (wid == 0) {
;       dt_l[2 * lane] = a0; dt_l[2 * lane + 1] = a1;
;       float s = (a0 + a1) * Ah;
; #pragma unroll
;       for (int o = 1; o < 64; o <<= 1) { float v = shfl_idx_f(s, (lane - o) & 63); if (lane >= o) s += v; }
;       acum_l[2 * lane + 1] = s; acum_l[2 * lane] = s - a1 * Ah;
.LBB0_570:
	v_cvt_pk_bf16_f32 v80, v64, v65
	v_cvt_pk_bf16_f32 v81, v66, v67
	s_barrier
	ds_write_b64 v219, v[80:81]
	v_cvt_pk_bf16_f32 v80, v76, v77
	v_cvt_pk_bf16_f32 v81, v78, v79
	v_readlane_b32 s84, v251, 58
	ds_write_b64 v219, v[80:81] offset:4352
	v_cvt_pk_bf16_f32 v80, v72, v73
	v_cvt_pk_bf16_f32 v81, v74, v75
	v_readlane_b32 s85, v251, 59
	ds_write_b64 v219, v[80:81] offset:8704
	v_cvt_pk_bf16_f32 v80, v68, v69
	v_cvt_pk_bf16_f32 v81, v70, v71
	s_and_b64 vcc, exec, s[84:85]
	ds_write_b64 v219, v[80:81] offset:13056
	s_cbranch_vccnz .LBB0_572
	v_add_f32_e32 v80, v148, v149
	v_mul_f32_e64 v81, v80, -v193
	ds_write_b64 v200, v[148:149]
	s_nop 1
	v_add_f32_dpp v81, v81, v81 row_shr:1 row_mask:0xf bank_mask:0xf
	s_nop 1
	v_add_f32_dpp v81, v81, v81 row_shr:2 row_mask:0xf bank_mask:0xf
	s_nop 1
	v_add_f32_dpp v81, v81, v81 row_shr:4 row_mask:0xf bank_mask:0xf
	s_nop 1
	v_add_f32_dpp v81, v81, v81 row_shr:8 row_mask:0xf bank_mask:0xf
	s_nop 1
	v_add_f32_dpp v81, v81, v81 row_bcast:15 row_mask:0xa bank_mask:0xf
	s_nop 1
	v_add_f32_dpp v81, v81, v81 row_bcast:31 row_mask:0xc bank_mask:0xf
	s_nop 1
	v_fma_f32 v80, v193, v149, v81
	ds_write_b64 v201, v[80:81]
